# layer-1 projection weight conversion runs in the prologue phase (the kernel's small-grid placement) instead of at the tail of layer 0's mixer phase
# speedup vs baseline: 1.0046x; 1.0025x over previous
.LBB0_58:
	s_cmpk_gt_i32 s65, 0x45f
	s_mov_b64 s[6:7], -1
	s_cbranch_scc0 .LBB0_70
	s_load_dword s4, s[2:3], 0x10
	s_load_dword s10, s[2:3], 0x0
	s_waitcnt lgkmcnt(0)
	s_lshr_b32 s4, s4, 16
	s_cmp_lg_u32 s4, 0
	s_cselect_b64 s[6:7], -1, 0
	s_cmp_lg_u64 s[6:7], 0
	s_addc_u32 s4, s10, 0
	s_cmpk_lt_u32 s4, 0x7fff
	s_cbranch_scc0 .LBB0_69
	s_add_i32 s8, s65, 0xfffffba0
	s_cmpk_gt_u32 s8, 0x35f
	s_mov_b64 s[6:7], -1
	s_cbranch_scc0 .LBB0_64
	s_add_i32 s4, s65, 0xfffff840
	s_lshr_b32 s4, s4, 4
	s_lshl_b64 s[6:7], s[4:5], 18
	s_add_u32 s6, s66, s6
	s_addc_u32 s7, s67, s7
	s_and_b32 s9, s65, 15
	v_mov_b32_e32 v1, v0
	s_lshl_b32 s10, s9, 8
	s_add_u32 s6, s6, s10
	v_ashrrev_i32_e32 v4, 6, v1
	v_and_b32_e32 v5, 63, v1
	v_lshlrev_b32_e32 v2, 2, v5
	s_addc_u32 s7, s7, 0
	v_ashrrev_i32_e32 v9, 31, v4
	v_mov_b32_e32 v8, v4
	v_lshl_add_u64 v[6:7], s[6:7], 0, v[2:3]
	v_lshlrev_b64 v[8:9], 12, v[8:9]
	v_lshl_add_u64 v[6:7], v[6:7], 0, v[8:9]
	v_add_co_u32_e32 v8, vcc, s41, v6
	s_mul_i32 s9, s9, 0x22000
	s_nop 0
	v_addc_co_u32_e32 v9, vcc, 0, v7, vcc
	v_add_co_u32_e32 v10, vcc, s43, v6
	s_add_u32 s7, s84, s9
	s_nop 0
	v_addc_co_u32_e32 v11, vcc, 0, v7, vcc
	v_add_co_u32_e32 v12, vcc, s45, v6
	s_addc_u32 s9, s85, 0
	s_nop 0
	v_addc_co_u32_e32 v13, vcc, 0, v7, vcc
	v_add_co_u32_e32 v16, vcc, s49, v6
	s_lshl_b32 s4, s4, 7
	s_nop 0
	v_addc_co_u32_e32 v17, vcc, 0, v7, vcc
	v_add_co_u32_e32 v18, vcc, s50, v6
	v_mov_b32_e32 v1, v4
	s_nop 0
	v_addc_co_u32_e32 v19, vcc, 0, v7, vcc
	v_add_co_u32_e32 v20, vcc, s51, v6
	s_mov_b32 s6, 0
	s_nop 0
	v_addc_co_u32_e32 v21, vcc, 0, v7, vcc
	v_add_co_u32_e32 v22, vcc, s52, v6
	s_nop 1
	v_addc_co_u32_e32 v23, vcc, 0, v7, vcc
	global_load_dword v15, v[6:7], off
	global_load_dword v24, v[8:9], off
	global_load_dword v25, v[10:11], off
	global_load_dword v26, v[12:13], off
	global_load_dword v27, v[16:17], off
	global_load_dword v28, v[18:19], off
	global_load_dword v29, v[20:21], off
	global_load_dword v30, v[22:23], off
	v_add_co_u32_e32 v8, vcc, s53, v6
	s_nop 1
	v_addc_co_u32_e32 v9, vcc, 0, v7, vcc
	v_add_co_u32_e32 v10, vcc, s54, v6
	s_nop 1
	v_addc_co_u32_e32 v11, vcc, 0, v7, vcc
	v_add_co_u32_e32 v12, vcc, s55, v6
	s_nop 1
	v_addc_co_u32_e32 v13, vcc, 0, v7, vcc
	v_add_co_u32_e32 v16, vcc, s56, v6
	s_nop 1
	v_addc_co_u32_e32 v17, vcc, 0, v7, vcc
	v_add_co_u32_e32 v18, vcc, s57, v6
	s_nop 1
	v_addc_co_u32_e32 v19, vcc, 0, v7, vcc
	v_add_co_u32_e32 v20, vcc, s58, v6
	s_nop 1
	v_addc_co_u32_e32 v21, vcc, 0, v7, vcc
	v_add_co_u32_e32 v22, vcc, s59, v6
	s_nop 1
	v_addc_co_u32_e32 v23, vcc, 0, v7, vcc
	v_add_co_u32_e32 v6, vcc, s60, v6
	s_nop 1
	v_addc_co_u32_e32 v7, vcc, 0, v7, vcc
	global_load_dword v8, v[8:9], off
	s_nop 0
	global_load_dword v9, v[10:11], off
	s_nop 0
	global_load_dword v10, v[12:13], off
	global_load_dword v11, v[16:17], off
	s_nop 0
	global_load_dword v12, v[18:19], off
	global_load_dword v13, v[20:21], off
	global_load_dword v16, v[22:23], off
	global_load_dword v17, v[6:7], off
	v_mad_u64_u32 v[6:7], s[10:11], v4, s38, v[2:3]
	s_add_u32 s10, s7, s4
	s_addc_u32 s11, s9, 0
	s_mov_b32 s4, 1
	s_mov_b32 s7, 16
	s_waitcnt vmcnt(15)
	ds_write_b32 v6, v15
	s_waitcnt vmcnt(14)
	ds_write_b32 v6, v24 offset:1040
	s_waitcnt vmcnt(13)
	ds_write_b32 v6, v25 offset:2080
	s_waitcnt vmcnt(12)
	ds_write_b32 v6, v26 offset:3120
	s_waitcnt vmcnt(11)
	ds_write_b32 v6, v27 offset:4160
	s_waitcnt vmcnt(10)
	ds_write_b32 v6, v28 offset:5200
	s_waitcnt vmcnt(9)
	ds_write_b32 v6, v29 offset:6240
	s_waitcnt vmcnt(8)
	ds_write_b32 v6, v30 offset:7280
	s_waitcnt vmcnt(7)
	ds_write_b32 v6, v8 offset:8320
	s_waitcnt vmcnt(6)
	ds_write_b32 v6, v9 offset:9360
	s_waitcnt vmcnt(5)
	ds_write_b32 v6, v10 offset:10400
	s_waitcnt vmcnt(4)
	ds_write_b32 v6, v11 offset:11440
	s_waitcnt vmcnt(3)
	ds_write_b32 v6, v12 offset:12480
	s_waitcnt vmcnt(2)
	ds_write_b32 v6, v13 offset:13520
	s_waitcnt vmcnt(1)
	ds_write_b32 v6, v16 offset:14560
	s_waitcnt vmcnt(0)
	ds_write_b32 v6, v17 offset:15600
	v_lshl_or_b32 v12, v5, 8, v2
	v_lshlrev_b32_e32 v2, 1, v5
	v_lshl_add_u64 v[6:7], s[10:11], 0, v[2:3]
	v_add_u32_e32 v2, 8, v4
	v_add_u32_e32 v8, 16, v4
	v_add_u32_e32 v10, 24, v4
	v_mov_b32_e32 v5, v2
	v_mov_b32_e32 v9, v8
	v_mov_b32_e32 v11, v10
	s_waitcnt lgkmcnt(0)
	s_barrier

.LBB0_1015:
	s_or_b64 exec, exec, s[0:1]
	v_readlane_b32 s0, v207, 39
	v_readlane_b32 s1, v207, 40
	s_andn2_b64 vcc, exec, s[0:1]
	s_waitcnt lgkmcnt(0)
	s_barrier
	s_cbranch_vccnz .LBB0_1263
	v_readlane_b32 s3, v206, 46
	v_readlane_b32 s0, v207, 3
	v_readlane_b32 s1, v207, 4
	v_cvt_f32_u32_e32 v1, s3
	s_load_dword s6, s[0:1], 0x0
	s_mov_b32 s0, 0x3fb8aa3b
	v_readlane_b32 s12, v208, 17
	v_mul_f32_e32 v1, 0xbe99999a, v1
	v_mul_f32_e32 v2, 0x3fb8aa3b, v1
	v_fma_f32 v3, v1, s0, -v2
	v_rndne_f32_e32 v4, v2
	s_waitcnt lgkmcnt(0)
	s_cmpk_lt_i32 s6, 0x100
	v_fmac_f32_e32 v3, 0x32a5705f, v1
	v_sub_f32_e32 v2, v2, v4
	v_add_f32_e32 v2, v2, v3
	s_cselect_b64 s[0:1], -1, 0
	v_exp_f32_e32 v2, v2
	v_cvt_i32_f32_e32 v3, v4
	v_writelane_b32 v205, s0, 11
	s_lshl_b32 s2, s3, 16
	s_lshl_b32 s82, s3, 7
	v_writelane_b32 v205, s1, 12
	s_lshl_b32 s0, s3, 2
	v_writelane_b32 v205, s0, 13
	s_mov_b32 s0, 0xc2ce8ed0
	v_writelane_b32 v205, s2, 14
	s_lshl_b32 s2, s3, 9
	v_ldexp_f32 v2, v2, v3
	v_cmp_ngt_f32_e32 vcc, s0, v1
	s_mov_b32 s0, 0x42b17218
	s_or_b32 s2, s2, 0xffffc000
	v_cndmask_b32_e32 v2, 0, v2, vcc
	v_cmp_nlt_f32_e32 vcc, s0, v1
	s_lshl_b32 s0, s3, 6
	s_lshl_b32 s4, s3, 1
	v_writelane_b32 v205, s2, 15
	s_lshl_b64 s[2:3], s[82:83], 2
	v_readlane_b32 s14, v208, 19
	s_mov_b32 s1, s83
	v_readlane_b32 s15, v208, 20
	s_add_u32 s94, s14, s2
	v_readlane_b32 s16, v208, 21
	s_addc_u32 s95, s15, s3
	s_lshl_b64 s[0:1], s[0:1], 2
	v_readlane_b32 s17, v208, 22
	s_add_u32 s0, s16, s0
	s_addc_u32 s1, s17, s1
	v_writelane_b32 v205, s0, 16
	v_readlane_b32 s2, v207, 54
	v_readlane_b32 s3, v207, 55
	v_writelane_b32 v205, s1, 17
	s_add_i32 s0, s6, 0xffffff80
	s_cmpk_gt_i32 s6, 0x7fff
	v_writelane_b32 v206, s0, 55
	s_cselect_b64 s[0:1], -1, 0
	s_and_b64 s[0:1], s[0:1], s[2:3]
	v_readlane_b32 s2, v206, 47
	v_readlane_b32 s3, v206, 48
	s_and_b64 s[0:1], s[0:1], s[2:3]
	v_writelane_b32 v205, s0, 18
	s_mov_b32 s5, s83
	v_readlane_b32 s2, v206, 10
	v_writelane_b32 v205, s1, 19
	v_readlane_b32 s0, v206, 5
	s_or_b32 s82, s4, s0
	v_readlane_b32 s3, v206, 11
	v_writelane_b32 v205, s4, 7
	s_or_b32 s2, s2, s4
	s_lshl_b64 s[0:1], s[82:83], 16
	v_writelane_b32 v205, s5, 8
	s_lshl_b64 s[2:3], s[2:3], 16
	v_readlane_b32 s4, v206, 16
	s_add_u32 s4, s4, s0
	v_readlane_b32 s0, v206, 17
	s_addc_u32 s5, s0, s1
	v_readlane_b32 s0, v206, 27
	v_writelane_b32 v205, s4, 20
	s_add_u32 s2, s0, s2
	v_readlane_b32 s0, v206, 29
	v_writelane_b32 v205, s5, 21
	s_addc_u32 s3, s0, s3
	v_writelane_b32 v205, s2, 22
	s_lshl_b32 s90, s6, 4
	s_add_i32 s0, s90, 0xfffff800
	v_writelane_b32 v205, s3, 23
	s_lshl_b32 s2, s6, 6
	s_lshl_b32 s1, s6, 5
	v_writelane_b32 v205, s0, 24
	s_add_i32 s0, s2, 0xffffe000
	v_cndmask_b32_e32 v1, v148, v2, vcc
	v_writelane_b32 v205, s0, 25
	s_add_i32 s0, s1, 0xfffff000
	s_waitcnt vmcnt(10)
	v_fmamk_f32 v86, v1, 0xbf19999a, v138
	v_writelane_b32 v205, s0, 26
	s_mov_b32 s0, 0
	v_writelane_b32 v206, s6, 53
	v_sub_f32_e32 v113, 1.0, v86
	v_writelane_b32 v205, s0, 27
	v_writelane_b32 v206, s2, 57
	v_readlane_b32 s13, v208, 18
	v_readlane_b32 s18, v208, 23
	v_readlane_b32 s19, v208, 24
	v_readlane_b32 s20, v208, 25
	v_readlane_b32 s21, v208, 26
	v_readlane_b32 s22, v208, 27
	v_readlane_b32 s23, v208, 28
	v_readlane_b32 s24, v208, 29
	v_readlane_b32 s25, v208, 30
	v_readlane_b32 s26, v208, 31
	v_readlane_b32 s27, v208, 32
	v_writelane_b32 v205, s90, 28
	v_writelane_b32 v206, s1, 59
	s_branch .LBB0_1018
